# out-proj K loop: B fragments of a half read ahead into spare quads, counted lgkmcnt waits (was read->wait->4 MFMA x8 per K step)
# speedup vs baseline: 1.0164x; 1.0104x over previous
.LBB0_80:
	ds_read_b128 v[114:117], v127 offset:16384
	ds_read_b128 v[118:121], v0
	ds_read_b128 v[166:169], v127 offset:18432
	ds_read_b128 v[170:173], v127 offset:20480
	ds_read_b128 v[174:177], v127 offset:22528
	ds_read_b128 v[238:241], v0 offset:2048
	ds_read_b128 v[242:245], v0 offset:4096
	ds_read_b128 v[246:249], v0 offset:6144
	s_andn2_b64 vcc, exec, s[38:39]
	s_waitcnt lgkmcnt(3)
	v_mfma_f32_16x16x32_bf16 v[78:81], v[114:117], v[118:121], v[78:81]
	ds_read_b128 v[230:233], v129 offset:16384
	ds_read_b128 v[234:237], v129 offset:22528
	v_mfma_f32_16x16x32_bf16 v[74:77], v[166:169], v[118:121], v[74:77]
	v_mfma_f32_16x16x32_bf16 v[70:73], v[170:173], v[118:121], v[70:73]
	v_mfma_f32_16x16x32_bf16 v[66:69], v[174:177], v[118:121], v[66:69]
	s_waitcnt lgkmcnt(4)
	v_mfma_f32_16x16x32_bf16 v[62:65], v[114:117], v[238:241], v[62:65]
	v_mfma_f32_16x16x32_bf16 v[58:61], v[166:169], v[238:241], v[58:61]
	v_mfma_f32_16x16x32_bf16 v[54:57], v[170:173], v[238:241], v[54:57]
	v_mfma_f32_16x16x32_bf16 v[50:53], v[174:177], v[238:241], v[50:53]
	ds_read_b128 v[238:241], v128 offset:2048
	s_waitcnt lgkmcnt(4)
	v_mfma_f32_16x16x32_bf16 v[218:221], v[114:117], v[242:245], v[46:49]
	v_mfma_f32_16x16x32_bf16 v[222:225], v[166:169], v[242:245], v[42:45]
	v_mfma_f32_16x16x32_bf16 v[226:229], v[170:173], v[242:245], v[38:41]
	v_mfma_f32_16x16x32_bf16 v[118:121], v[174:177], v[242:245], v[34:37]
	s_nop 2
	ds_read_b128 v[34:37], v128
	ds_read_b128 v[242:245], v128 offset:4096
	s_waitcnt lgkmcnt(5)
	v_mfma_f32_16x16x32_bf16 v[114:117], v[114:117], v[246:249], v[30:33]
	v_mfma_f32_16x16x32_bf16 v[166:169], v[166:169], v[246:249], v[26:29]
	v_mfma_f32_16x16x32_bf16 v[170:173], v[170:173], v[246:249], v[22:25]
	v_mfma_f32_16x16x32_bf16 v[18:21], v[174:177], v[246:249], v[18:21]
	ds_read_b128 v[174:177], v129 offset:20480
	ds_read_b128 v[246:249], v128 offset:6144
	s_waitcnt lgkmcnt(2)
	v_mfma_f32_16x16x32_bf16 v[22:25], v[230:233], v[34:37], v[78:81]
	s_nop 2
	ds_read_b128 v[78:81], v129 offset:18432
	s_waitcnt lgkmcnt(0)
	v_mfma_f32_16x16x32_bf16 v[26:29], v[78:81], v[34:37], v[74:77]
	v_mfma_f32_16x16x32_bf16 v[30:33], v[174:177], v[34:37], v[70:73]
	v_mfma_f32_16x16x32_bf16 v[34:37], v[234:237], v[34:37], v[66:69]
	v_mfma_f32_16x16x32_bf16 v[38:41], v[230:233], v[238:241], v[62:65]
	v_mfma_f32_16x16x32_bf16 v[42:45], v[78:81], v[238:241], v[58:61]
	v_mfma_f32_16x16x32_bf16 v[46:49], v[174:177], v[238:241], v[54:57]
	v_mfma_f32_16x16x32_bf16 v[50:53], v[234:237], v[238:241], v[50:53]
	v_mfma_f32_16x16x32_bf16 v[54:57], v[230:233], v[242:245], v[218:221]
	v_mfma_f32_16x16x32_bf16 v[58:61], v[78:81], v[242:245], v[222:225]
	v_mfma_f32_16x16x32_bf16 v[62:65], v[174:177], v[242:245], v[226:229]
	v_mfma_f32_16x16x32_bf16 v[66:69], v[234:237], v[242:245], v[118:121]
	v_mfma_f32_16x16x32_bf16 v[70:73], v[230:233], v[246:249], v[114:117]
	v_mfma_f32_16x16x32_bf16 v[74:77], v[78:81], v[246:249], v[166:169]
	v_mfma_f32_16x16x32_bf16 v[78:81], v[174:177], v[246:249], v[170:173]
	v_mfma_f32_16x16x32_bf16 v[18:21], v[234:237], v[246:249], v[18:21]
	s_cbranch_vccnz .LBB0_82
	s_waitcnt vmcnt(0)
	ds_write_b16 v130, v2 offset:36864
	ds_write_b16_d16_hi v130, v2 offset:36992
	ds_write_b16 v131, v3 offset:36864
	ds_write_b16_d16_hi v132, v3 offset:36864
	ds_write_b16 v133, v4 offset:36864
	ds_write_b16_d16_hi v134, v4 offset:36864
	ds_write_b16 v135, v5 offset:36864
	ds_write_b16_d16_hi v136, v5 offset:36864
	ds_write_b16 v137, v6 offset:36864
	ds_write_b16_d16_hi v137, v6 offset:36992
	ds_write_b16 v138, v7 offset:36864
	ds_write_b16_d16_hi v139, v7 offset:36864
	ds_write_b16 v140, v8 offset:36864
	ds_write_b16_d16_hi v141, v8 offset:36864
	ds_write_b16 v142, v9 offset:36864
	ds_write_b16_d16_hi v143, v9 offset:36864
	ds_write_b16 v144, v10 offset:36864
	ds_write_b16_d16_hi v144, v10 offset:36992
	ds_write_b16 v145, v11 offset:36864
	ds_write_b16_d16_hi v154, v11 offset:36864
	ds_write_b16 v155, v12 offset:36864
	ds_write_b16_d16_hi v156, v12 offset:36864
	ds_write_b16 v157, v13 offset:36864
	ds_write_b16_d16_hi v158, v13 offset:36864
	ds_write_b16 v159, v14 offset:36864
	ds_write_b16_d16_hi v159, v14 offset:36992
	ds_write_b16 v160, v15 offset:36864
	ds_write_b16_d16_hi v161, v15 offset:36864
	ds_write_b16 v162, v16 offset:36864
	ds_write_b16_d16_hi v163, v16 offset:36864
	ds_write_b16 v164, v17 offset:36864
	ds_write_b16_d16_hi v165, v17 offset:36864

.LBB0_87:
	ds_read_b128 v[106:109], v127 offset:53248
	ds_read_b128 v[110:113], v0 offset:36864
	ds_read_b128 v[114:117], v127 offset:55296
	ds_read_b128 v[118:121], v127 offset:57344
	ds_read_b128 v[166:169], v127 offset:59392
	ds_read_b128 v[238:241], v0 offset:38912
	ds_read_b128 v[242:245], v0 offset:40960
	ds_read_b128 v[246:249], v0 offset:43008
	s_andn2_b64 vcc, exec, s[40:41]
	s_waitcnt lgkmcnt(3)
	v_mfma_f32_16x16x32_bf16 v[22:25], v[106:109], v[110:113], v[22:25]
	ds_read_b128 v[222:225], v129 offset:53248
	ds_read_b128 v[226:229], v129 offset:59392
	v_mfma_f32_16x16x32_bf16 v[26:29], v[114:117], v[110:113], v[26:29]
	v_mfma_f32_16x16x32_bf16 v[30:33], v[118:121], v[110:113], v[30:33]
	v_mfma_f32_16x16x32_bf16 v[34:37], v[166:169], v[110:113], v[34:37]
	s_waitcnt lgkmcnt(4)
	v_mfma_f32_16x16x32_bf16 v[38:41], v[106:109], v[238:241], v[38:41]
	v_mfma_f32_16x16x32_bf16 v[42:45], v[114:117], v[238:241], v[42:45]
	v_mfma_f32_16x16x32_bf16 v[46:49], v[118:121], v[238:241], v[46:49]
	v_mfma_f32_16x16x32_bf16 v[50:53], v[166:169], v[238:241], v[50:53]
	ds_read_b128 v[238:241], v128 offset:38912
	s_waitcnt lgkmcnt(4)
	v_mfma_f32_16x16x32_bf16 v[170:173], v[106:109], v[242:245], v[54:57]
	v_mfma_f32_16x16x32_bf16 v[174:177], v[114:117], v[242:245], v[58:61]
	v_mfma_f32_16x16x32_bf16 v[218:221], v[118:121], v[242:245], v[62:65]
	v_mfma_f32_16x16x32_bf16 v[110:113], v[166:169], v[242:245], v[66:69]
	s_nop 2
	ds_read_b128 v[54:57], v128 offset:36864
	ds_read_b128 v[242:245], v128 offset:40960
	s_waitcnt lgkmcnt(5)
	v_mfma_f32_16x16x32_bf16 v[106:109], v[106:109], v[246:249], v[70:73]
	v_mfma_f32_16x16x32_bf16 v[114:117], v[114:117], v[246:249], v[74:77]
	v_mfma_f32_16x16x32_bf16 v[118:121], v[118:121], v[246:249], v[78:81]
	v_mfma_f32_16x16x32_bf16 v[18:21], v[166:169], v[246:249], v[18:21]
	ds_read_b128 v[166:169], v129 offset:57344
	ds_read_b128 v[246:249], v128 offset:43008
	s_waitcnt lgkmcnt(2)
	v_mfma_f32_16x16x32_bf16 v[78:81], v[222:225], v[54:57], v[22:25]
	s_nop 2
	ds_read_b128 v[22:25], v129 offset:55296
	s_waitcnt lgkmcnt(0)
	v_mfma_f32_16x16x32_bf16 v[74:77], v[22:25], v[54:57], v[26:29]
	v_mfma_f32_16x16x32_bf16 v[70:73], v[166:169], v[54:57], v[30:33]
	v_mfma_f32_16x16x32_bf16 v[66:69], v[226:229], v[54:57], v[34:37]
	v_mfma_f32_16x16x32_bf16 v[62:65], v[222:225], v[238:241], v[38:41]
	v_mfma_f32_16x16x32_bf16 v[58:61], v[22:25], v[238:241], v[42:45]
	v_mfma_f32_16x16x32_bf16 v[54:57], v[166:169], v[238:241], v[46:49]
	v_mfma_f32_16x16x32_bf16 v[50:53], v[226:229], v[238:241], v[50:53]
	v_mfma_f32_16x16x32_bf16 v[34:37], v[226:229], v[242:245], v[110:113]
	v_mfma_f32_16x16x32_bf16 v[46:49], v[222:225], v[242:245], v[170:173]
	v_mfma_f32_16x16x32_bf16 v[42:45], v[22:25], v[242:245], v[174:177]
	v_mfma_f32_16x16x32_bf16 v[38:41], v[166:169], v[242:245], v[218:221]
	v_mfma_f32_16x16x32_bf16 v[30:33], v[222:225], v[246:249], v[106:109]
	v_mfma_f32_16x16x32_bf16 v[26:29], v[22:25], v[246:249], v[114:117]
	v_mfma_f32_16x16x32_bf16 v[22:25], v[166:169], v[246:249], v[118:121]
	v_mfma_f32_16x16x32_bf16 v[18:21], v[226:229], v[246:249], v[18:21]
	s_cbranch_vccnz .LBB0_75
	s_waitcnt vmcnt(0)
	ds_write_b16 v130, v2
	ds_write_b16_d16_hi v130, v2 offset:128
	ds_write_b16 v131, v3
	ds_write_b16_d16_hi v132, v3
	ds_write_b16 v133, v4
	ds_write_b16_d16_hi v134, v4
	ds_write_b16 v135, v5
	ds_write_b16_d16_hi v136, v5
	ds_write_b16 v137, v6
	ds_write_b16_d16_hi v137, v6 offset:128
	ds_write_b16 v138, v7
	ds_write_b16_d16_hi v139, v7
	ds_write_b16 v140, v8
	ds_write_b16_d16_hi v141, v8
	ds_write_b16 v142, v9
	ds_write_b16_d16_hi v143, v9
	ds_write_b16 v144, v10
	ds_write_b16_d16_hi v144, v10 offset:128
	ds_write_b16 v145, v11
	ds_write_b16_d16_hi v154, v11
	ds_write_b16 v155, v12
	ds_write_b16_d16_hi v156, v12
	ds_write_b16 v157, v13
	ds_write_b16_d16_hi v158, v13
	ds_write_b16 v159, v14
	ds_write_b16_d16_hi v159, v14 offset:128
	ds_write_b16 v160, v15
	ds_write_b16_d16_hi v161, v15
	ds_write_b16 v162, v16
	ds_write_b16_d16_hi v163, v16
	ds_write_b16 v164, v17
	ds_write_b16_d16_hi v165, v17
	s_branch .LBB0_75
